# adds hand-written prenorm to transposer + combine + row phases
# speedup vs baseline: 1.0203x; 1.0015x over previous
.LBB0_223:
.LBB0_224:
	s_waitcnt vmcnt(0) lgkmcnt(0)
	s_load_dwordx2 s[0:1], s[92:93], 0x40
	s_load_dwordx2 s[2:3], s[92:93], 0x38
	s_load_dwordx2 s[4:5], s[92:93], 0xf0
	s_load_dwordx2 s[6:7], s[92:93], 0x0
	s_load_dwordx2 s[8:9], s[92:93], 0x8
	v_and_b32_e32 v2, 63, v154
	v_lshlrev_b32_e32 v1, 4, v2
	v_lshlrev_b32_e32 v2, 3, v2
	v_mov_b32_e32 v6, 1.0
	v_mov_b32_e32 v7, 1.0
	s_mov_b32 s40, 0x3a000000
	s_mov_b32 s41, 0x358637bd
	v_readfirstlane_b32 s10, v154
	s_lshr_b32 s10, s10, 6
	s_lshl_b32 s12, s96, 3
	s_add_u32 s10, s10, s12
	s_waitcnt lgkmcnt(0)
	s_add_u32 s12, s10, 0
	s_lshl_b32 s13, s12, 13
	s_lshl_b32 s14, s12, 12
	s_add_u32 s20, s6, s13
	s_addc_u32 s21, s7, 0
	s_add_u32 s22, s90, 0x21918000
	s_addc_u32 s23, s91, 0
	s_add_u32 s22, s22, s14
	s_addc_u32 s23, s23, 0
	s_add_u32 s36, s20, 0x1000
	s_addc_u32 s37, s21, 0
	global_load_dwordx4 v[34:37], v1, s[20:21]
	global_load_dwordx4 v[38:41], v1, s[20:21] offset:1024
	global_load_dwordx4 v[42:45], v1, s[20:21] offset:2048
	global_load_dwordx4 v[46:49], v1, s[20:21] offset:3072
	global_load_dwordx4 v[50:53], v1, s[36:37]
	global_load_dwordx4 v[54:57], v1, s[36:37] offset:1024
	global_load_dwordx4 v[58:61], v1, s[36:37] offset:2048
	global_load_dwordx4 v[62:65], v1, s[36:37] offset:3072
	s_mov_b32 s16, 4
	s_add_u32 s17, s16, 0
	s_mul_i32 s17, s17, 49152
	s_add_u32 s17, s17, 0x10404000
	s_add_u32 s28, s90, s17
	s_addc_u32 s29, s91, 0
	s_add_u32 s17, s16, 0
	s_mul_i32 s17, s17, 49152
	s_add_u32 s17, s17, 0x10400000
	s_add_u32 s30, s90, s17
	s_addc_u32 s31, s91, 0
	s_add_u32 s32, s30, 0x2000
	s_addc_u32 s33, s31, 0
	s_add_u32 s18, s2, 0x1000
	s_addc_u32 s19, s3, 0
	global_load_dwordx4 v[130:133], v1, s[2:3]
	global_load_dwordx4 v[134:137], v1, s[2:3] offset:1024
	global_load_dwordx4 v[138:141], v1, s[2:3] offset:2048
	global_load_dwordx4 v[142:145], v1, s[2:3] offset:3072
	global_load_dwordx4 v[146:149], v1, s[18:19]
	global_load_dwordx4 v[150:153], v1, s[18:19] offset:1024
	global_load_dwordx4 v[156:159], v1, s[18:19] offset:2048
	global_load_dwordx4 v[160:163], v1, s[18:19] offset:3072
	s_add_u32 s18, s30, 0x1000
	s_addc_u32 s19, s31, 0
	global_load_dwordx4 v[164:167], v1, s[30:31]
	global_load_dwordx4 v[168:171], v1, s[30:31] offset:1024
	global_load_dwordx4 v[172:175], v1, s[30:31] offset:2048
	global_load_dwordx4 v[176:179], v1, s[30:31] offset:3072
	global_load_dwordx4 v[180:183], v1, s[18:19]
	global_load_dwordx4 v[184:187], v1, s[18:19] offset:1024
	global_load_dwordx4 v[188:191], v1, s[18:19] offset:2048
	global_load_dwordx4 v[192:195], v1, s[18:19] offset:3072
	s_add_u32 s18, s32, 0x1000
	s_addc_u32 s19, s33, 0
	global_load_dwordx4 v[196:199], v1, s[32:33]
	global_load_dwordx4 v[200:203], v1, s[32:33] offset:1024
	global_load_dwordx4 v[204:207], v1, s[32:33] offset:2048
	global_load_dwordx4 v[208:211], v1, s[32:33] offset:3072
	global_load_dwordx4 v[212:215], v1, s[18:19]
	global_load_dwordx4 v[216:219], v1, s[18:19] offset:1024
	global_load_dwordx4 v[220:223], v1, s[18:19] offset:2048
	global_load_dwordx4 v[224:227], v1, s[18:19] offset:3072
	s_add_u32 s12, s10, 2048
	s_lshl_b32 s13, s12, 13
	s_lshl_b32 s14, s12, 12
	s_add_u32 s20, s6, s13
	s_addc_u32 s21, s7, 0
	s_add_u32 s22, s90, 0x21918000
	s_addc_u32 s23, s91, 0
	s_add_u32 s22, s22, s14
	s_addc_u32 s23, s23, 0
	s_add_u32 s36, s20, 0x1000
	s_addc_u32 s37, s21, 0
	global_load_dwordx4 v[66:69], v1, s[20:21]
	global_load_dwordx4 v[70:73], v1, s[20:21] offset:1024
	global_load_dwordx4 v[74:77], v1, s[20:21] offset:2048
	global_load_dwordx4 v[78:81], v1, s[20:21] offset:3072
	global_load_dwordx4 v[82:85], v1, s[36:37]
	global_load_dwordx4 v[86:89], v1, s[36:37] offset:1024
	global_load_dwordx4 v[90:93], v1, s[36:37] offset:2048
	global_load_dwordx4 v[94:97], v1, s[36:37] offset:3072
	s_add_u32 s12, s10, 0
	s_lshl_b32 s14, s12, 12
	s_add_u32 s26, s90, 0x11918000
	s_addc_u32 s27, s91, 0
	s_add_u32 s26, s26, s14
	s_addc_u32 s27, s27, 0
	s_waitcnt vmcnt(32)
	v_mov_b32_e32 v8, 0
	v_fmac_f32_e32 v8, v34, v34
	v_fmac_f32_e32 v8, v35, v35
	v_fmac_f32_e32 v8, v36, v36
	v_fmac_f32_e32 v8, v37, v37
	v_fmac_f32_e32 v8, v38, v38
	v_fmac_f32_e32 v8, v39, v39
	v_fmac_f32_e32 v8, v40, v40
	v_fmac_f32_e32 v8, v41, v41
	v_fmac_f32_e32 v8, v42, v42
	v_fmac_f32_e32 v8, v43, v43
	v_fmac_f32_e32 v8, v44, v44
	v_fmac_f32_e32 v8, v45, v45
	v_fmac_f32_e32 v8, v46, v46
	v_fmac_f32_e32 v8, v47, v47
	v_fmac_f32_e32 v8, v48, v48
	v_fmac_f32_e32 v8, v49, v49
	v_fmac_f32_e32 v8, v50, v50
	v_fmac_f32_e32 v8, v51, v51
	v_fmac_f32_e32 v8, v52, v52
	v_fmac_f32_e32 v8, v53, v53
	v_fmac_f32_e32 v8, v54, v54
	v_fmac_f32_e32 v8, v55, v55
	v_fmac_f32_e32 v8, v56, v56
	v_fmac_f32_e32 v8, v57, v57
	v_fmac_f32_e32 v8, v58, v58
	v_fmac_f32_e32 v8, v59, v59
	v_fmac_f32_e32 v8, v60, v60
	v_fmac_f32_e32 v8, v61, v61
	v_fmac_f32_e32 v8, v62, v62
	v_fmac_f32_e32 v8, v63, v63
	v_fmac_f32_e32 v8, v64, v64
	v_fmac_f32_e32 v8, v65, v65
	s_nop 1
	v_add_f32_dpp v8, v8, v8 quad_perm:[1,0,3,2] row_mask:0xf bank_mask:0xf
	s_nop 1
	v_add_f32_dpp v8, v8, v8 quad_perm:[2,3,0,1] row_mask:0xf bank_mask:0xf
	s_nop 1
	v_add_f32_dpp v8, v8, v8 row_ror:4 row_mask:0xf bank_mask:0xf
	s_nop 1
	v_add_f32_dpp v8, v8, v8 row_ror:8 row_mask:0xf bank_mask:0xf
	s_nop 1
	v_readlane_b32 s42, v8, 0
	v_readlane_b32 s43, v8, 16
	v_readlane_b32 s44, v8, 32
	v_readlane_b32 s45, v8, 48
	s_nop 1
	v_mov_b32_e32 v8, s42
	v_add_f32_e32 v8, s43, v8
	v_add_f32_e32 v8, s44, v8
	v_add_f32_e32 v8, s45, v8
	v_mov_b32_e32 v4, s41
	v_fmac_f32_e32 v4, s40, v8
	v_rsq_f32_e32 v4, v4
	s_nop 0
	v_mov_b32_e32 v5, v4
	s_waitcnt vmcnt(8)
	v_pk_mul_f32 v[10:11], v[34:35], v[4:5]
	v_pk_mul_f32 v[10:11], v[10:11], v[130:131]
	v_pk_add_f32 v[12:13], v[196:197], v[6:7]
	v_pk_fma_f32 v[14:15], v[10:11], v[12:13], v[164:165]
	v_pk_mul_f32 v[10:11], v[36:37], v[4:5]
	v_pk_mul_f32 v[10:11], v[10:11], v[132:133]
	v_pk_add_f32 v[12:13], v[198:199], v[6:7]
	v_pk_fma_f32 v[16:17], v[10:11], v[12:13], v[166:167]
	v_cvt_pk_bf16_f32 v26, v14, v15
	v_cvt_pk_bf16_f32 v27, v16, v17
	global_store_dwordx2 v2, v[26:27], s[26:27]
	v_pk_mul_f32 v[10:11], v[38:39], v[4:5]
	v_pk_mul_f32 v[10:11], v[10:11], v[134:135]
	v_pk_add_f32 v[12:13], v[200:201], v[6:7]
	v_pk_fma_f32 v[14:15], v[10:11], v[12:13], v[168:169]
	v_pk_mul_f32 v[10:11], v[40:41], v[4:5]
	v_pk_mul_f32 v[10:11], v[10:11], v[136:137]
	v_pk_add_f32 v[12:13], v[202:203], v[6:7]
	v_pk_fma_f32 v[16:17], v[10:11], v[12:13], v[170:171]
	v_cvt_pk_bf16_f32 v28, v14, v15
	v_cvt_pk_bf16_f32 v29, v16, v17
	global_store_dwordx2 v2, v[28:29], s[26:27] offset:512
	v_pk_mul_f32 v[10:11], v[42:43], v[4:5]
	v_pk_mul_f32 v[10:11], v[10:11], v[138:139]
	v_pk_add_f32 v[12:13], v[204:205], v[6:7]
	v_pk_fma_f32 v[14:15], v[10:11], v[12:13], v[172:173]
	v_pk_mul_f32 v[10:11], v[44:45], v[4:5]
	v_pk_mul_f32 v[10:11], v[10:11], v[140:141]
	v_pk_add_f32 v[12:13], v[206:207], v[6:7]
	v_pk_fma_f32 v[16:17], v[10:11], v[12:13], v[174:175]
	v_cvt_pk_bf16_f32 v30, v14, v15
	v_cvt_pk_bf16_f32 v31, v16, v17
	global_store_dwordx2 v2, v[30:31], s[26:27] offset:1024
	v_pk_mul_f32 v[10:11], v[46:47], v[4:5]
	v_pk_mul_f32 v[10:11], v[10:11], v[142:143]
	v_pk_add_f32 v[12:13], v[208:209], v[6:7]
	v_pk_fma_f32 v[14:15], v[10:11], v[12:13], v[176:177]
	v_pk_mul_f32 v[10:11], v[48:49], v[4:5]
	v_pk_mul_f32 v[10:11], v[10:11], v[144:145]
	v_pk_add_f32 v[12:13], v[210:211], v[6:7]
	v_pk_fma_f32 v[16:17], v[10:11], v[12:13], v[178:179]
	v_cvt_pk_bf16_f32 v32, v14, v15
	v_cvt_pk_bf16_f32 v33, v16, v17
	global_store_dwordx2 v2, v[32:33], s[26:27] offset:1536
	v_pk_mul_f32 v[10:11], v[50:51], v[4:5]
	v_pk_mul_f32 v[10:11], v[10:11], v[146:147]
	v_pk_add_f32 v[12:13], v[212:213], v[6:7]
	v_pk_fma_f32 v[14:15], v[10:11], v[12:13], v[180:181]
	v_pk_mul_f32 v[10:11], v[52:53], v[4:5]
	v_pk_mul_f32 v[10:11], v[10:11], v[148:149]
	v_pk_add_f32 v[12:13], v[214:215], v[6:7]
	v_pk_fma_f32 v[16:17], v[10:11], v[12:13], v[182:183]
	v_cvt_pk_bf16_f32 v26, v14, v15
	v_cvt_pk_bf16_f32 v27, v16, v17
	global_store_dwordx2 v2, v[26:27], s[26:27] offset:2048
	v_pk_mul_f32 v[10:11], v[54:55], v[4:5]
	v_pk_mul_f32 v[10:11], v[10:11], v[150:151]
	v_pk_add_f32 v[12:13], v[216:217], v[6:7]
	v_pk_fma_f32 v[14:15], v[10:11], v[12:13], v[184:185]
	v_pk_mul_f32 v[10:11], v[56:57], v[4:5]
	v_pk_mul_f32 v[10:11], v[10:11], v[152:153]
	v_pk_add_f32 v[12:13], v[218:219], v[6:7]
	v_pk_fma_f32 v[16:17], v[10:11], v[12:13], v[186:187]
	v_cvt_pk_bf16_f32 v28, v14, v15
	v_cvt_pk_bf16_f32 v29, v16, v17
	global_store_dwordx2 v2, v[28:29], s[26:27] offset:2560
	v_pk_mul_f32 v[10:11], v[58:59], v[4:5]
	v_pk_mul_f32 v[10:11], v[10:11], v[156:157]
	v_pk_add_f32 v[12:13], v[220:221], v[6:7]
	v_pk_fma_f32 v[14:15], v[10:11], v[12:13], v[188:189]
	v_pk_mul_f32 v[10:11], v[60:61], v[4:5]
	v_pk_mul_f32 v[10:11], v[10:11], v[158:159]
	v_pk_add_f32 v[12:13], v[222:223], v[6:7]
	v_pk_fma_f32 v[16:17], v[10:11], v[12:13], v[190:191]
	v_cvt_pk_bf16_f32 v30, v14, v15
	v_cvt_pk_bf16_f32 v31, v16, v17
	global_store_dwordx2 v2, v[30:31], s[26:27] offset:3072
	v_pk_mul_f32 v[10:11], v[62:63], v[4:5]
	v_pk_mul_f32 v[10:11], v[10:11], v[160:161]
	v_pk_add_f32 v[12:13], v[224:225], v[6:7]
	v_pk_fma_f32 v[14:15], v[10:11], v[12:13], v[192:193]
	v_pk_mul_f32 v[10:11], v[64:65], v[4:5]
	v_pk_mul_f32 v[10:11], v[10:11], v[162:163]
	v_pk_add_f32 v[12:13], v[226:227], v[6:7]
	v_pk_fma_f32 v[16:17], v[10:11], v[12:13], v[194:195]
	v_cvt_pk_bf16_f32 v32, v14, v15
	v_cvt_pk_bf16_f32 v33, v16, v17
	global_store_dwordx2 v2, v[32:33], s[26:27] offset:3584
	s_mov_b32 s16, 4
	s_add_u32 s17, s16, 0
	s_mul_i32 s17, s17, 49152
	s_add_u32 s17, s17, 0x10404000
	s_add_u32 s28, s90, s17
	s_addc_u32 s29, s91, 0
	s_add_u32 s17, s16, 0
	s_mul_i32 s17, s17, 49152
	s_add_u32 s17, s17, 0x10400000
	s_add_u32 s30, s90, s17
	s_addc_u32 s31, s91, 0
	s_add_u32 s32, s30, 0x2000
	s_addc_u32 s33, s31, 0
	s_add_u32 s18, s2, 0x1000
	s_addc_u32 s19, s3, 0
	global_load_dwordx4 v[130:133], v1, s[2:3]
	global_load_dwordx4 v[134:137], v1, s[2:3] offset:1024
	global_load_dwordx4 v[138:141], v1, s[2:3] offset:2048
	global_load_dwordx4 v[142:145], v1, s[2:3] offset:3072
	global_load_dwordx4 v[146:149], v1, s[18:19]
	global_load_dwordx4 v[150:153], v1, s[18:19] offset:1024
	global_load_dwordx4 v[156:159], v1, s[18:19] offset:2048
	global_load_dwordx4 v[160:163], v1, s[18:19] offset:3072
	s_add_u32 s18, s30, 0x1000
	s_addc_u32 s19, s31, 0
	global_load_dwordx4 v[164:167], v1, s[30:31]
	global_load_dwordx4 v[168:171], v1, s[30:31] offset:1024
	global_load_dwordx4 v[172:175], v1, s[30:31] offset:2048
	global_load_dwordx4 v[176:179], v1, s[30:31] offset:3072
	global_load_dwordx4 v[180:183], v1, s[18:19]
	global_load_dwordx4 v[184:187], v1, s[18:19] offset:1024
	global_load_dwordx4 v[188:191], v1, s[18:19] offset:2048
	global_load_dwordx4 v[192:195], v1, s[18:19] offset:3072
	s_add_u32 s18, s32, 0x1000
	s_addc_u32 s19, s33, 0
	global_load_dwordx4 v[196:199], v1, s[32:33]
	global_load_dwordx4 v[200:203], v1, s[32:33] offset:1024
	global_load_dwordx4 v[204:207], v1, s[32:33] offset:2048
	global_load_dwordx4 v[208:211], v1, s[32:33] offset:3072
	global_load_dwordx4 v[212:215], v1, s[18:19]
	global_load_dwordx4 v[216:219], v1, s[18:19] offset:1024
	global_load_dwordx4 v[220:223], v1, s[18:19] offset:2048
	global_load_dwordx4 v[224:227], v1, s[18:19] offset:3072
	s_add_u32 s12, s10, 4096
	s_lshl_b32 s13, s12, 13
	s_lshl_b32 s14, s12, 12
	s_sub_u32 s15, s13, 0x2000000
	s_add_u32 s20, s8, s15
	s_addc_u32 s21, s9, 0
	s_add_u32 s22, s90, 0x21918000
	s_addc_u32 s23, s91, 0
	s_add_u32 s22, s22, s14
	s_addc_u32 s23, s23, 0
	s_add_u32 s36, s20, 0x1000
	s_addc_u32 s37, s21, 0
	global_load_dwordx4 v[34:37], v1, s[20:21]
	global_load_dwordx4 v[38:41], v1, s[20:21] offset:1024
	global_load_dwordx4 v[42:45], v1, s[20:21] offset:2048
	global_load_dwordx4 v[46:49], v1, s[20:21] offset:3072
	global_load_dwordx4 v[50:53], v1, s[36:37]
	global_load_dwordx4 v[54:57], v1, s[36:37] offset:1024
	global_load_dwordx4 v[58:61], v1, s[36:37] offset:2048
	global_load_dwordx4 v[62:65], v1, s[36:37] offset:3072
	s_add_u32 s12, s10, 2048
	s_lshl_b32 s14, s12, 12
	s_add_u32 s26, s90, 0x11918000
	s_addc_u32 s27, s91, 0
	s_add_u32 s26, s26, s14
	s_addc_u32 s27, s27, 0
	s_waitcnt vmcnt(40)
	v_mov_b32_e32 v8, 0
	v_fmac_f32_e32 v8, v66, v66
	v_fmac_f32_e32 v8, v67, v67
	v_fmac_f32_e32 v8, v68, v68
	v_fmac_f32_e32 v8, v69, v69
	v_fmac_f32_e32 v8, v70, v70
	v_fmac_f32_e32 v8, v71, v71
	v_fmac_f32_e32 v8, v72, v72
	v_fmac_f32_e32 v8, v73, v73
	v_fmac_f32_e32 v8, v74, v74
	v_fmac_f32_e32 v8, v75, v75
	v_fmac_f32_e32 v8, v76, v76
	v_fmac_f32_e32 v8, v77, v77
	v_fmac_f32_e32 v8, v78, v78
	v_fmac_f32_e32 v8, v79, v79
	v_fmac_f32_e32 v8, v80, v80
	v_fmac_f32_e32 v8, v81, v81
	v_fmac_f32_e32 v8, v82, v82
	v_fmac_f32_e32 v8, v83, v83
	v_fmac_f32_e32 v8, v84, v84
	v_fmac_f32_e32 v8, v85, v85
	v_fmac_f32_e32 v8, v86, v86
	v_fmac_f32_e32 v8, v87, v87
	v_fmac_f32_e32 v8, v88, v88
	v_fmac_f32_e32 v8, v89, v89
	v_fmac_f32_e32 v8, v90, v90
	v_fmac_f32_e32 v8, v91, v91
	v_fmac_f32_e32 v8, v92, v92
	v_fmac_f32_e32 v8, v93, v93
	v_fmac_f32_e32 v8, v94, v94
	v_fmac_f32_e32 v8, v95, v95
	v_fmac_f32_e32 v8, v96, v96
	v_fmac_f32_e32 v8, v97, v97
	s_nop 1
	v_add_f32_dpp v8, v8, v8 quad_perm:[1,0,3,2] row_mask:0xf bank_mask:0xf
	s_nop 1
	v_add_f32_dpp v8, v8, v8 quad_perm:[2,3,0,1] row_mask:0xf bank_mask:0xf
	s_nop 1
	v_add_f32_dpp v8, v8, v8 row_ror:4 row_mask:0xf bank_mask:0xf
	s_nop 1
	v_add_f32_dpp v8, v8, v8 row_ror:8 row_mask:0xf bank_mask:0xf
	s_nop 1
	v_readlane_b32 s42, v8, 0
	v_readlane_b32 s43, v8, 16
	v_readlane_b32 s44, v8, 32
	v_readlane_b32 s45, v8, 48
	s_nop 1
	v_mov_b32_e32 v8, s42
	v_add_f32_e32 v8, s43, v8
	v_add_f32_e32 v8, s44, v8
	v_add_f32_e32 v8, s45, v8
	v_mov_b32_e32 v4, s41
	v_fmac_f32_e32 v4, s40, v8
	v_rsq_f32_e32 v4, v4
	s_nop 0
	v_mov_b32_e32 v5, v4
	s_waitcnt vmcnt(8)
	v_pk_mul_f32 v[10:11], v[66:67], v[4:5]
	v_pk_mul_f32 v[10:11], v[10:11], v[130:131]
	v_pk_add_f32 v[12:13], v[196:197], v[6:7]
	v_pk_fma_f32 v[14:15], v[10:11], v[12:13], v[164:165]
	v_pk_mul_f32 v[10:11], v[68:69], v[4:5]
	v_pk_mul_f32 v[10:11], v[10:11], v[132:133]
	v_pk_add_f32 v[12:13], v[198:199], v[6:7]
	v_pk_fma_f32 v[16:17], v[10:11], v[12:13], v[166:167]
	v_cvt_pk_bf16_f32 v26, v14, v15
	v_cvt_pk_bf16_f32 v27, v16, v17
	global_store_dwordx2 v2, v[26:27], s[26:27]
	v_pk_mul_f32 v[10:11], v[70:71], v[4:5]
	v_pk_mul_f32 v[10:11], v[10:11], v[134:135]
	v_pk_add_f32 v[12:13], v[200:201], v[6:7]
	v_pk_fma_f32 v[14:15], v[10:11], v[12:13], v[168:169]
	v_pk_mul_f32 v[10:11], v[72:73], v[4:5]
	v_pk_mul_f32 v[10:11], v[10:11], v[136:137]
	v_pk_add_f32 v[12:13], v[202:203], v[6:7]
	v_pk_fma_f32 v[16:17], v[10:11], v[12:13], v[170:171]
	v_cvt_pk_bf16_f32 v28, v14, v15
	v_cvt_pk_bf16_f32 v29, v16, v17
	global_store_dwordx2 v2, v[28:29], s[26:27] offset:512
	v_pk_mul_f32 v[10:11], v[74:75], v[4:5]
	v_pk_mul_f32 v[10:11], v[10:11], v[138:139]
	v_pk_add_f32 v[12:13], v[204:205], v[6:7]
	v_pk_fma_f32 v[14:15], v[10:11], v[12:13], v[172:173]
	v_pk_mul_f32 v[10:11], v[76:77], v[4:5]
	v_pk_mul_f32 v[10:11], v[10:11], v[140:141]
	v_pk_add_f32 v[12:13], v[206:207], v[6:7]
	v_pk_fma_f32 v[16:17], v[10:11], v[12:13], v[174:175]
	v_cvt_pk_bf16_f32 v30, v14, v15
	v_cvt_pk_bf16_f32 v31, v16, v17
	global_store_dwordx2 v2, v[30:31], s[26:27] offset:1024
	v_pk_mul_f32 v[10:11], v[78:79], v[4:5]
	v_pk_mul_f32 v[10:11], v[10:11], v[142:143]
	v_pk_add_f32 v[12:13], v[208:209], v[6:7]
	v_pk_fma_f32 v[14:15], v[10:11], v[12:13], v[176:177]
	v_pk_mul_f32 v[10:11], v[80:81], v[4:5]
	v_pk_mul_f32 v[10:11], v[10:11], v[144:145]
	v_pk_add_f32 v[12:13], v[210:211], v[6:7]
	v_pk_fma_f32 v[16:17], v[10:11], v[12:13], v[178:179]
	v_cvt_pk_bf16_f32 v32, v14, v15
	v_cvt_pk_bf16_f32 v33, v16, v17
	global_store_dwordx2 v2, v[32:33], s[26:27] offset:1536
	v_pk_mul_f32 v[10:11], v[82:83], v[4:5]
	v_pk_mul_f32 v[10:11], v[10:11], v[146:147]
	v_pk_add_f32 v[12:13], v[212:213], v[6:7]
	v_pk_fma_f32 v[14:15], v[10:11], v[12:13], v[180:181]
	v_pk_mul_f32 v[10:11], v[84:85], v[4:5]
	v_pk_mul_f32 v[10:11], v[10:11], v[148:149]
	v_pk_add_f32 v[12:13], v[214:215], v[6:7]
	v_pk_fma_f32 v[16:17], v[10:11], v[12:13], v[182:183]
	v_cvt_pk_bf16_f32 v26, v14, v15
	v_cvt_pk_bf16_f32 v27, v16, v17
	global_store_dwordx2 v2, v[26:27], s[26:27] offset:2048
	v_pk_mul_f32 v[10:11], v[86:87], v[4:5]
	v_pk_mul_f32 v[10:11], v[10:11], v[150:151]
	v_pk_add_f32 v[12:13], v[216:217], v[6:7]
	v_pk_fma_f32 v[14:15], v[10:11], v[12:13], v[184:185]
	v_pk_mul_f32 v[10:11], v[88:89], v[4:5]
	v_pk_mul_f32 v[10:11], v[10:11], v[152:153]
	v_pk_add_f32 v[12:13], v[218:219], v[6:7]
	v_pk_fma_f32 v[16:17], v[10:11], v[12:13], v[186:187]
	v_cvt_pk_bf16_f32 v28, v14, v15
	v_cvt_pk_bf16_f32 v29, v16, v17
	global_store_dwordx2 v2, v[28:29], s[26:27] offset:2560
	v_pk_mul_f32 v[10:11], v[90:91], v[4:5]
	v_pk_mul_f32 v[10:11], v[10:11], v[156:157]
	v_pk_add_f32 v[12:13], v[220:221], v[6:7]
	v_pk_fma_f32 v[14:15], v[10:11], v[12:13], v[188:189]
	v_pk_mul_f32 v[10:11], v[92:93], v[4:5]
	v_pk_mul_f32 v[10:11], v[10:11], v[158:159]
	v_pk_add_f32 v[12:13], v[222:223], v[6:7]
	v_pk_fma_f32 v[16:17], v[10:11], v[12:13], v[190:191]
	v_cvt_pk_bf16_f32 v30, v14, v15
	v_cvt_pk_bf16_f32 v31, v16, v17
	global_store_dwordx2 v2, v[30:31], s[26:27] offset:3072
	v_pk_mul_f32 v[10:11], v[94:95], v[4:5]
	v_pk_mul_f32 v[10:11], v[10:11], v[160:161]
	v_pk_add_f32 v[12:13], v[224:225], v[6:7]
	v_pk_fma_f32 v[14:15], v[10:11], v[12:13], v[192:193]
	v_pk_mul_f32 v[10:11], v[96:97], v[4:5]
	v_pk_mul_f32 v[10:11], v[10:11], v[162:163]
	v_pk_add_f32 v[12:13], v[226:227], v[6:7]
	v_pk_fma_f32 v[16:17], v[10:11], v[12:13], v[194:195]
	v_cvt_pk_bf16_f32 v32, v14, v15
	v_cvt_pk_bf16_f32 v33, v16, v17
	global_store_dwordx2 v2, v[32:33], s[26:27] offset:3584
	s_lshr_b32 s16, s10, 10
	s_add_u32 s17, s16, 0
	s_mul_i32 s17, s17, 49152
	s_add_u32 s17, s17, 0x10404000
	s_add_u32 s28, s90, s17
	s_addc_u32 s29, s91, 0
	s_add_u32 s17, s16, 0
	s_mul_i32 s17, s17, 49152
	s_add_u32 s17, s17, 0x10400000
	s_add_u32 s30, s90, s17
	s_addc_u32 s31, s91, 0
	s_add_u32 s32, s30, 0x2000
	s_addc_u32 s33, s31, 0
	s_add_u32 s18, s2, 0x1000
	s_addc_u32 s19, s3, 0
	global_load_dwordx4 v[130:133], v1, s[2:3]
	global_load_dwordx4 v[134:137], v1, s[2:3] offset:1024
	global_load_dwordx4 v[138:141], v1, s[2:3] offset:2048
	global_load_dwordx4 v[142:145], v1, s[2:3] offset:3072
	global_load_dwordx4 v[146:149], v1, s[18:19]
	global_load_dwordx4 v[150:153], v1, s[18:19] offset:1024
	global_load_dwordx4 v[156:159], v1, s[18:19] offset:2048
	global_load_dwordx4 v[160:163], v1, s[18:19] offset:3072
	s_add_u32 s18, s30, 0x1000
	s_addc_u32 s19, s31, 0
	global_load_dwordx4 v[164:167], v1, s[30:31]
	global_load_dwordx4 v[168:171], v1, s[30:31] offset:1024
	global_load_dwordx4 v[172:175], v1, s[30:31] offset:2048
	global_load_dwordx4 v[176:179], v1, s[30:31] offset:3072
	global_load_dwordx4 v[180:183], v1, s[18:19]
	global_load_dwordx4 v[184:187], v1, s[18:19] offset:1024
	global_load_dwordx4 v[188:191], v1, s[18:19] offset:2048
	global_load_dwordx4 v[192:195], v1, s[18:19] offset:3072
	s_add_u32 s18, s32, 0x1000
	s_addc_u32 s19, s33, 0
	global_load_dwordx4 v[196:199], v1, s[32:33]
	global_load_dwordx4 v[200:203], v1, s[32:33] offset:1024
	global_load_dwordx4 v[204:207], v1, s[32:33] offset:2048
	global_load_dwordx4 v[208:211], v1, s[32:33] offset:3072
	global_load_dwordx4 v[212:215], v1, s[18:19]
	global_load_dwordx4 v[216:219], v1, s[18:19] offset:1024
	global_load_dwordx4 v[220:223], v1, s[18:19] offset:2048
	global_load_dwordx4 v[224:227], v1, s[18:19] offset:3072
	s_add_u32 s12, s10, 6144
	s_lshl_b32 s13, s12, 13
	s_lshl_b32 s14, s12, 12
	s_sub_u32 s15, s13, 0x2000000
	s_add_u32 s20, s8, s15
	s_addc_u32 s21, s9, 0
	s_add_u32 s22, s90, 0x21918000
	s_addc_u32 s23, s91, 0
	s_add_u32 s22, s22, s14
	s_addc_u32 s23, s23, 0
	s_add_u32 s36, s20, 0x1000
	s_addc_u32 s37, s21, 0
	global_load_dwordx4 v[66:69], v1, s[20:21]
	global_load_dwordx4 v[70:73], v1, s[20:21] offset:1024
	global_load_dwordx4 v[74:77], v1, s[20:21] offset:2048
	global_load_dwordx4 v[78:81], v1, s[20:21] offset:3072
	global_load_dwordx4 v[82:85], v1, s[36:37]
	global_load_dwordx4 v[86:89], v1, s[36:37] offset:1024
	global_load_dwordx4 v[90:93], v1, s[36:37] offset:2048
	global_load_dwordx4 v[94:97], v1, s[36:37] offset:3072
	s_add_u32 s12, s10, 4096
	s_lshl_b32 s14, s12, 12
	s_add_u32 s26, s90, 0x11918000
	s_addc_u32 s27, s91, 0
	s_add_u32 s26, s26, s14
	s_addc_u32 s27, s27, 0
	s_waitcnt vmcnt(40)
	v_mov_b32_e32 v8, 0
	v_fmac_f32_e32 v8, v34, v34
	v_fmac_f32_e32 v8, v35, v35
	v_fmac_f32_e32 v8, v36, v36
	v_fmac_f32_e32 v8, v37, v37
	v_fmac_f32_e32 v8, v38, v38
	v_fmac_f32_e32 v8, v39, v39
	v_fmac_f32_e32 v8, v40, v40
	v_fmac_f32_e32 v8, v41, v41
	v_fmac_f32_e32 v8, v42, v42
	v_fmac_f32_e32 v8, v43, v43
	v_fmac_f32_e32 v8, v44, v44
	v_fmac_f32_e32 v8, v45, v45
	v_fmac_f32_e32 v8, v46, v46
	v_fmac_f32_e32 v8, v47, v47
	v_fmac_f32_e32 v8, v48, v48
	v_fmac_f32_e32 v8, v49, v49
	v_fmac_f32_e32 v8, v50, v50
	v_fmac_f32_e32 v8, v51, v51
	v_fmac_f32_e32 v8, v52, v52
	v_fmac_f32_e32 v8, v53, v53
	v_fmac_f32_e32 v8, v54, v54
	v_fmac_f32_e32 v8, v55, v55
	v_fmac_f32_e32 v8, v56, v56
	v_fmac_f32_e32 v8, v57, v57
	v_fmac_f32_e32 v8, v58, v58
	v_fmac_f32_e32 v8, v59, v59
	v_fmac_f32_e32 v8, v60, v60
	v_fmac_f32_e32 v8, v61, v61
	v_fmac_f32_e32 v8, v62, v62
	v_fmac_f32_e32 v8, v63, v63
	v_fmac_f32_e32 v8, v64, v64
	v_fmac_f32_e32 v8, v65, v65
	s_nop 1
	v_add_f32_dpp v8, v8, v8 quad_perm:[1,0,3,2] row_mask:0xf bank_mask:0xf
	s_nop 1
	v_add_f32_dpp v8, v8, v8 quad_perm:[2,3,0,1] row_mask:0xf bank_mask:0xf
	s_nop 1
	v_add_f32_dpp v8, v8, v8 row_ror:4 row_mask:0xf bank_mask:0xf
	s_nop 1
	v_add_f32_dpp v8, v8, v8 row_ror:8 row_mask:0xf bank_mask:0xf
	s_nop 1
	v_readlane_b32 s42, v8, 0
	v_readlane_b32 s43, v8, 16
	v_readlane_b32 s44, v8, 32
	v_readlane_b32 s45, v8, 48
	s_nop 1
	v_mov_b32_e32 v8, s42
	v_add_f32_e32 v8, s43, v8
	v_add_f32_e32 v8, s44, v8
	v_add_f32_e32 v8, s45, v8
	v_mov_b32_e32 v4, s41
	v_fmac_f32_e32 v4, s40, v8
	v_rsq_f32_e32 v4, v4
	s_nop 0
	v_mov_b32_e32 v5, v4
	s_waitcnt vmcnt(8)
	v_pk_mul_f32 v[10:11], v[34:35], v[4:5]
	v_pk_mul_f32 v[10:11], v[10:11], v[130:131]
	v_pk_add_f32 v[12:13], v[196:197], v[6:7]
	v_pk_fma_f32 v[14:15], v[10:11], v[12:13], v[164:165]
	v_pk_mul_f32 v[10:11], v[36:37], v[4:5]
	v_pk_mul_f32 v[10:11], v[10:11], v[132:133]
	v_pk_add_f32 v[12:13], v[198:199], v[6:7]
	v_pk_fma_f32 v[16:17], v[10:11], v[12:13], v[166:167]
	v_cvt_pk_bf16_f32 v26, v14, v15
	v_cvt_pk_bf16_f32 v27, v16, v17
	global_store_dwordx2 v2, v[26:27], s[26:27]
	v_pk_mul_f32 v[10:11], v[38:39], v[4:5]
	v_pk_mul_f32 v[10:11], v[10:11], v[134:135]
	v_pk_add_f32 v[12:13], v[200:201], v[6:7]
	v_pk_fma_f32 v[14:15], v[10:11], v[12:13], v[168:169]
	v_pk_mul_f32 v[10:11], v[40:41], v[4:5]
	v_pk_mul_f32 v[10:11], v[10:11], v[136:137]
	v_pk_add_f32 v[12:13], v[202:203], v[6:7]
	v_pk_fma_f32 v[16:17], v[10:11], v[12:13], v[170:171]
	v_cvt_pk_bf16_f32 v28, v14, v15
	v_cvt_pk_bf16_f32 v29, v16, v17
	global_store_dwordx2 v2, v[28:29], s[26:27] offset:512
	v_pk_mul_f32 v[10:11], v[42:43], v[4:5]
	v_pk_mul_f32 v[10:11], v[10:11], v[138:139]
	v_pk_add_f32 v[12:13], v[204:205], v[6:7]
	v_pk_fma_f32 v[14:15], v[10:11], v[12:13], v[172:173]
	v_pk_mul_f32 v[10:11], v[44:45], v[4:5]
	v_pk_mul_f32 v[10:11], v[10:11], v[140:141]
	v_pk_add_f32 v[12:13], v[206:207], v[6:7]
	v_pk_fma_f32 v[16:17], v[10:11], v[12:13], v[174:175]
	v_cvt_pk_bf16_f32 v30, v14, v15
	v_cvt_pk_bf16_f32 v31, v16, v17
	global_store_dwordx2 v2, v[30:31], s[26:27] offset:1024
	v_pk_mul_f32 v[10:11], v[46:47], v[4:5]
	v_pk_mul_f32 v[10:11], v[10:11], v[142:143]
	v_pk_add_f32 v[12:13], v[208:209], v[6:7]
	v_pk_fma_f32 v[14:15], v[10:11], v[12:13], v[176:177]
	v_pk_mul_f32 v[10:11], v[48:49], v[4:5]
	v_pk_mul_f32 v[10:11], v[10:11], v[144:145]
	v_pk_add_f32 v[12:13], v[210:211], v[6:7]
	v_pk_fma_f32 v[16:17], v[10:11], v[12:13], v[178:179]
	v_cvt_pk_bf16_f32 v32, v14, v15
	v_cvt_pk_bf16_f32 v33, v16, v17
	global_store_dwordx2 v2, v[32:33], s[26:27] offset:1536
	v_pk_mul_f32 v[10:11], v[50:51], v[4:5]
	v_pk_mul_f32 v[10:11], v[10:11], v[146:147]
	v_pk_add_f32 v[12:13], v[212:213], v[6:7]
	v_pk_fma_f32 v[14:15], v[10:11], v[12:13], v[180:181]
	v_pk_mul_f32 v[10:11], v[52:53], v[4:5]
	v_pk_mul_f32 v[10:11], v[10:11], v[148:149]
	v_pk_add_f32 v[12:13], v[214:215], v[6:7]
	v_pk_fma_f32 v[16:17], v[10:11], v[12:13], v[182:183]
	v_cvt_pk_bf16_f32 v26, v14, v15
	v_cvt_pk_bf16_f32 v27, v16, v17
	global_store_dwordx2 v2, v[26:27], s[26:27] offset:2048
	v_pk_mul_f32 v[10:11], v[54:55], v[4:5]
	v_pk_mul_f32 v[10:11], v[10:11], v[150:151]
	v_pk_add_f32 v[12:13], v[216:217], v[6:7]
	v_pk_fma_f32 v[14:15], v[10:11], v[12:13], v[184:185]
	v_pk_mul_f32 v[10:11], v[56:57], v[4:5]
	v_pk_mul_f32 v[10:11], v[10:11], v[152:153]
	v_pk_add_f32 v[12:13], v[218:219], v[6:7]
	v_pk_fma_f32 v[16:17], v[10:11], v[12:13], v[186:187]
	v_cvt_pk_bf16_f32 v28, v14, v15
	v_cvt_pk_bf16_f32 v29, v16, v17
	global_store_dwordx2 v2, v[28:29], s[26:27] offset:2560
	v_pk_mul_f32 v[10:11], v[58:59], v[4:5]
	v_pk_mul_f32 v[10:11], v[10:11], v[156:157]
	v_pk_add_f32 v[12:13], v[220:221], v[6:7]
	v_pk_fma_f32 v[14:15], v[10:11], v[12:13], v[188:189]
	v_pk_mul_f32 v[10:11], v[60:61], v[4:5]
	v_pk_mul_f32 v[10:11], v[10:11], v[158:159]
	v_pk_add_f32 v[12:13], v[222:223], v[6:7]
	v_pk_fma_f32 v[16:17], v[10:11], v[12:13], v[190:191]
	v_cvt_pk_bf16_f32 v30, v14, v15
	v_cvt_pk_bf16_f32 v31, v16, v17
	global_store_dwordx2 v2, v[30:31], s[26:27] offset:3072
	v_pk_mul_f32 v[10:11], v[62:63], v[4:5]
	v_pk_mul_f32 v[10:11], v[10:11], v[160:161]
	v_pk_add_f32 v[12:13], v[224:225], v[6:7]
	v_pk_fma_f32 v[14:15], v[10:11], v[12:13], v[192:193]
	v_pk_mul_f32 v[10:11], v[64:65], v[4:5]
	v_pk_mul_f32 v[10:11], v[10:11], v[162:163]
	v_pk_add_f32 v[12:13], v[226:227], v[6:7]
	v_pk_fma_f32 v[16:17], v[10:11], v[12:13], v[194:195]
	v_cvt_pk_bf16_f32 v32, v14, v15
	v_cvt_pk_bf16_f32 v33, v16, v17
	global_store_dwordx2 v2, v[32:33], s[26:27] offset:3584
	s_lshr_b32 s16, s10, 10
	s_add_u32 s16, s16, 2
	s_add_u32 s17, s16, 0
	s_mul_i32 s17, s17, 49152
	s_add_u32 s17, s17, 0x10404000
	s_add_u32 s28, s90, s17
	s_addc_u32 s29, s91, 0
	s_add_u32 s17, s16, 0
	s_mul_i32 s17, s17, 49152
	s_add_u32 s17, s17, 0x10400000
	s_add_u32 s30, s90, s17
	s_addc_u32 s31, s91, 0
	s_add_u32 s32, s30, 0x2000
	s_addc_u32 s33, s31, 0
	s_add_u32 s18, s2, 0x1000
	s_addc_u32 s19, s3, 0
	global_load_dwordx4 v[130:133], v1, s[2:3]
	global_load_dwordx4 v[134:137], v1, s[2:3] offset:1024
	global_load_dwordx4 v[138:141], v1, s[2:3] offset:2048
	global_load_dwordx4 v[142:145], v1, s[2:3] offset:3072
	global_load_dwordx4 v[146:149], v1, s[18:19]
	global_load_dwordx4 v[150:153], v1, s[18:19] offset:1024
	global_load_dwordx4 v[156:159], v1, s[18:19] offset:2048
	global_load_dwordx4 v[160:163], v1, s[18:19] offset:3072
	s_add_u32 s18, s30, 0x1000
	s_addc_u32 s19, s31, 0
	global_load_dwordx4 v[164:167], v1, s[30:31]
	global_load_dwordx4 v[168:171], v1, s[30:31] offset:1024
	global_load_dwordx4 v[172:175], v1, s[30:31] offset:2048
	global_load_dwordx4 v[176:179], v1, s[30:31] offset:3072
	global_load_dwordx4 v[180:183], v1, s[18:19]
	global_load_dwordx4 v[184:187], v1, s[18:19] offset:1024
	global_load_dwordx4 v[188:191], v1, s[18:19] offset:2048
	global_load_dwordx4 v[192:195], v1, s[18:19] offset:3072
	s_add_u32 s18, s32, 0x1000
	s_addc_u32 s19, s33, 0
	global_load_dwordx4 v[196:199], v1, s[32:33]
	global_load_dwordx4 v[200:203], v1, s[32:33] offset:1024
	global_load_dwordx4 v[204:207], v1, s[32:33] offset:2048
	global_load_dwordx4 v[208:211], v1, s[32:33] offset:3072
	global_load_dwordx4 v[212:215], v1, s[18:19]
	global_load_dwordx4 v[216:219], v1, s[18:19] offset:1024
	global_load_dwordx4 v[220:223], v1, s[18:19] offset:2048
	global_load_dwordx4 v[224:227], v1, s[18:19] offset:3072
	s_add_u32 s12, s10, 6144
	s_lshl_b32 s14, s12, 12
	s_add_u32 s26, s90, 0x11918000
	s_addc_u32 s27, s91, 0
	s_add_u32 s26, s26, s14
	s_addc_u32 s27, s27, 0
	s_waitcnt vmcnt(32)
	v_mov_b32_e32 v8, 0
	v_fmac_f32_e32 v8, v66, v66
	v_fmac_f32_e32 v8, v67, v67
	v_fmac_f32_e32 v8, v68, v68
	v_fmac_f32_e32 v8, v69, v69
	v_fmac_f32_e32 v8, v70, v70
	v_fmac_f32_e32 v8, v71, v71
	v_fmac_f32_e32 v8, v72, v72
	v_fmac_f32_e32 v8, v73, v73
	v_fmac_f32_e32 v8, v74, v74
	v_fmac_f32_e32 v8, v75, v75
	v_fmac_f32_e32 v8, v76, v76
	v_fmac_f32_e32 v8, v77, v77
	v_fmac_f32_e32 v8, v78, v78
	v_fmac_f32_e32 v8, v79, v79
	v_fmac_f32_e32 v8, v80, v80
	v_fmac_f32_e32 v8, v81, v81
	v_fmac_f32_e32 v8, v82, v82
	v_fmac_f32_e32 v8, v83, v83
	v_fmac_f32_e32 v8, v84, v84
	v_fmac_f32_e32 v8, v85, v85
	v_fmac_f32_e32 v8, v86, v86
	v_fmac_f32_e32 v8, v87, v87
	v_fmac_f32_e32 v8, v88, v88
	v_fmac_f32_e32 v8, v89, v89
	v_fmac_f32_e32 v8, v90, v90
	v_fmac_f32_e32 v8, v91, v91
	v_fmac_f32_e32 v8, v92, v92
	v_fmac_f32_e32 v8, v93, v93
	v_fmac_f32_e32 v8, v94, v94
	v_fmac_f32_e32 v8, v95, v95
	v_fmac_f32_e32 v8, v96, v96
	v_fmac_f32_e32 v8, v97, v97
	s_nop 1
	v_add_f32_dpp v8, v8, v8 quad_perm:[1,0,3,2] row_mask:0xf bank_mask:0xf
	s_nop 1
	v_add_f32_dpp v8, v8, v8 quad_perm:[2,3,0,1] row_mask:0xf bank_mask:0xf
	s_nop 1
	v_add_f32_dpp v8, v8, v8 row_ror:4 row_mask:0xf bank_mask:0xf
	s_nop 1
	v_add_f32_dpp v8, v8, v8 row_ror:8 row_mask:0xf bank_mask:0xf
	s_nop 1
	v_readlane_b32 s42, v8, 0
	v_readlane_b32 s43, v8, 16
	v_readlane_b32 s44, v8, 32
	v_readlane_b32 s45, v8, 48
	s_nop 1
	v_mov_b32_e32 v8, s42
	v_add_f32_e32 v8, s43, v8
	v_add_f32_e32 v8, s44, v8
	v_add_f32_e32 v8, s45, v8
	v_mov_b32_e32 v4, s41
	v_fmac_f32_e32 v4, s40, v8
	v_rsq_f32_e32 v4, v4
	s_nop 0
	v_mov_b32_e32 v5, v4
	s_waitcnt vmcnt(0)
	v_pk_mul_f32 v[10:11], v[66:67], v[4:5]
	v_pk_mul_f32 v[10:11], v[10:11], v[130:131]
	v_pk_add_f32 v[12:13], v[196:197], v[6:7]
	v_pk_fma_f32 v[14:15], v[10:11], v[12:13], v[164:165]
	v_pk_mul_f32 v[10:11], v[68:69], v[4:5]
	v_pk_mul_f32 v[10:11], v[10:11], v[132:133]
	v_pk_add_f32 v[12:13], v[198:199], v[6:7]
	v_pk_fma_f32 v[16:17], v[10:11], v[12:13], v[166:167]
	v_cvt_pk_bf16_f32 v26, v14, v15
	v_cvt_pk_bf16_f32 v27, v16, v17
	global_store_dwordx2 v2, v[26:27], s[26:27]
	v_pk_mul_f32 v[10:11], v[70:71], v[4:5]
	v_pk_mul_f32 v[10:11], v[10:11], v[134:135]
	v_pk_add_f32 v[12:13], v[200:201], v[6:7]
	v_pk_fma_f32 v[14:15], v[10:11], v[12:13], v[168:169]
	v_pk_mul_f32 v[10:11], v[72:73], v[4:5]
	v_pk_mul_f32 v[10:11], v[10:11], v[136:137]
	v_pk_add_f32 v[12:13], v[202:203], v[6:7]
	v_pk_fma_f32 v[16:17], v[10:11], v[12:13], v[170:171]
	v_cvt_pk_bf16_f32 v28, v14, v15
	v_cvt_pk_bf16_f32 v29, v16, v17
	global_store_dwordx2 v2, v[28:29], s[26:27] offset:512
	v_pk_mul_f32 v[10:11], v[74:75], v[4:5]
	v_pk_mul_f32 v[10:11], v[10:11], v[138:139]
	v_pk_add_f32 v[12:13], v[204:205], v[6:7]
	v_pk_fma_f32 v[14:15], v[10:11], v[12:13], v[172:173]
	v_pk_mul_f32 v[10:11], v[76:77], v[4:5]
	v_pk_mul_f32 v[10:11], v[10:11], v[140:141]
	v_pk_add_f32 v[12:13], v[206:207], v[6:7]
	v_pk_fma_f32 v[16:17], v[10:11], v[12:13], v[174:175]
	v_cvt_pk_bf16_f32 v30, v14, v15
	v_cvt_pk_bf16_f32 v31, v16, v17
	global_store_dwordx2 v2, v[30:31], s[26:27] offset:1024
	v_pk_mul_f32 v[10:11], v[78:79], v[4:5]
	v_pk_mul_f32 v[10:11], v[10:11], v[142:143]
	v_pk_add_f32 v[12:13], v[208:209], v[6:7]
	v_pk_fma_f32 v[14:15], v[10:11], v[12:13], v[176:177]
	v_pk_mul_f32 v[10:11], v[80:81], v[4:5]
	v_pk_mul_f32 v[10:11], v[10:11], v[144:145]
	v_pk_add_f32 v[12:13], v[210:211], v[6:7]
	v_pk_fma_f32 v[16:17], v[10:11], v[12:13], v[178:179]
	v_cvt_pk_bf16_f32 v32, v14, v15
	v_cvt_pk_bf16_f32 v33, v16, v17
	global_store_dwordx2 v2, v[32:33], s[26:27] offset:1536
	v_pk_mul_f32 v[10:11], v[82:83], v[4:5]
	v_pk_mul_f32 v[10:11], v[10:11], v[146:147]
	v_pk_add_f32 v[12:13], v[212:213], v[6:7]
	v_pk_fma_f32 v[14:15], v[10:11], v[12:13], v[180:181]
	v_pk_mul_f32 v[10:11], v[84:85], v[4:5]
	v_pk_mul_f32 v[10:11], v[10:11], v[148:149]
	v_pk_add_f32 v[12:13], v[214:215], v[6:7]
	v_pk_fma_f32 v[16:17], v[10:11], v[12:13], v[182:183]
	v_cvt_pk_bf16_f32 v26, v14, v15
	v_cvt_pk_bf16_f32 v27, v16, v17
	global_store_dwordx2 v2, v[26:27], s[26:27] offset:2048
	v_pk_mul_f32 v[10:11], v[86:87], v[4:5]
	v_pk_mul_f32 v[10:11], v[10:11], v[150:151]
	v_pk_add_f32 v[12:13], v[216:217], v[6:7]
	v_pk_fma_f32 v[14:15], v[10:11], v[12:13], v[184:185]
	v_pk_mul_f32 v[10:11], v[88:89], v[4:5]
	v_pk_mul_f32 v[10:11], v[10:11], v[152:153]
	v_pk_add_f32 v[12:13], v[218:219], v[6:7]
	v_pk_fma_f32 v[16:17], v[10:11], v[12:13], v[186:187]
	v_cvt_pk_bf16_f32 v28, v14, v15
	v_cvt_pk_bf16_f32 v29, v16, v17
	global_store_dwordx2 v2, v[28:29], s[26:27] offset:2560
	v_pk_mul_f32 v[10:11], v[90:91], v[4:5]
	v_pk_mul_f32 v[10:11], v[10:11], v[156:157]
	v_pk_add_f32 v[12:13], v[220:221], v[6:7]
	v_pk_fma_f32 v[14:15], v[10:11], v[12:13], v[188:189]
	v_pk_mul_f32 v[10:11], v[92:93], v[4:5]
	v_pk_mul_f32 v[10:11], v[10:11], v[158:159]
	v_pk_add_f32 v[12:13], v[222:223], v[6:7]
	v_pk_fma_f32 v[16:17], v[10:11], v[12:13], v[190:191]
	v_cvt_pk_bf16_f32 v30, v14, v15
	v_cvt_pk_bf16_f32 v31, v16, v17
	global_store_dwordx2 v2, v[30:31], s[26:27] offset:3072
	v_pk_mul_f32 v[10:11], v[94:95], v[4:5]
	v_pk_mul_f32 v[10:11], v[10:11], v[160:161]
	v_pk_add_f32 v[12:13], v[224:225], v[6:7]
	v_pk_fma_f32 v[14:15], v[10:11], v[12:13], v[192:193]
	v_pk_mul_f32 v[10:11], v[96:97], v[4:5]
	v_pk_mul_f32 v[10:11], v[10:11], v[162:163]
	v_pk_add_f32 v[12:13], v[226:227], v[6:7]
	v_pk_fma_f32 v[16:17], v[10:11], v[12:13], v[194:195]
	v_cvt_pk_bf16_f32 v32, v14, v15
	v_cvt_pk_bf16_f32 v33, v16, v17
	global_store_dwordx2 v2, v[32:33], s[26:27] offset:3584
	s_waitcnt vmcnt(0)
	s_branch .LBB0_231
